# P3 group start offset slept after the first attention unit has issued its Q loads and first K/V chunk DMA (loads land during the wait)
# speedup vs baseline: 1.0167x; 1.0001x over previous
; #define LAS __attribute__((address_space(3)))
; __device__ __forceinline__ bool attn_unit(const Ptrs& P, LAS unsigned char* lds, int unit, int tid, int wave, int lane, bool pre, int nxt) {
;     const int n = unit & 31, kh = (unit >> 5) & 3, b = unit >> 7;
;     const int g = wave & 3, q0 = 64 * (wave >> 2), h = kh * 4 + g, r = lane & 31, hh = lane >> 5;
;     unsigned char* ws = P.ws;
;     bf16_t* Qb = (bf16_t*)(ws + WS_Q) + (size_t)(b * SEQ + n * 128 + q0) * DM + h * 64;
;     const bf16_t* Kg = (const bf16_t*)(ws + WS_K) + (size_t)b * SEQ * KVW + kh * 64; const bf16_t* Vg = (const bf16_t*)(ws + WS_VT) + (size_t)(b * 4 + kh) * 64 * SEQ;
;     const bf16_t* Kcg = (const bf16_t*)(ws + WS_KC) + (size_t)b * CTX * KVW + kh * 64; const bf16_t* Vcg = (const bf16_t*)(ws + WS_VCT) + (size_t)(b * 4 + kh) * 64 * CTX;
;     float mq = fabsf(P.qg[lane]), mk = fabsf(P.kg[lane]);
; #pragma unroll
;     for (int o = 1; o < 64; o <<= 1) { mq = fmaxf(mq, __shfl_xor(mq, o)); mk = fmaxf(mk, __shfl_xor(mk, o)); }
;     const float sink2 = P.sink[h] * LOG2E; const float mshift = fmaxf(64.0f * QSCALE * mq * mk, sink2);
;     bf16x8_t qf[2][4];
; #pragma unroll
;     for (int cb = 0; cb < 2; ++cb)
; #pragma unroll
;         for (int ds = 0; ds < 4; ++ds) qf[cb][ds] = __builtin_nontemporal_load((const bf16x8_t*)(Qb + (size_t)(32 * cb + r) * DM + 16 * ds + 8 * hh));
;     f32x16 o[2][2];
; #pragma unroll
;     for (int db = 0; db < 2; ++db)
; #pragma unroll
;         for (int cb = 0; cb < 2; ++cb)
; #pragma unroll
;             for (int i = 0; i < 16; ++i) o[db][cb][i] = 0.f;
;     float rs[2] = {0.f, 0.f};
;     f32x16 negm;
; #pragma unroll
;     for (int i = 0; i < 16; ++i) negm[i] = -mshift;
; __device__ __forceinline__ void mk_p3(const Ptrs& P, LAS unsigned char* lds, int tid, int wave, int lane, int bx, int G, bool dry) {
;     ...
;         { bool pre = false; for (int u = bx; u < NB * 32 * 4; u += G) pre = attn_unit(P, lds, u, tid, wave, lane, pre, u + G < NB * 32 * 4 ? u + G : -1); }
.LBB9_305:
	s_cmp_lt_i32 s92, 4
	s_cselect_b64 s[2:3], -1, 0
	s_and_b64 s[22:23], s[2:3], s[0:1]
	s_andn2_b64 vcc, exec, s[22:23]
	s_cbranch_vccnz .LBB9_444
	v_writelane_b32 v251, s22, 33
	s_cmpk_gt_i32 s97, 0x1ff
	v_and_b32_e32 v171, 31, v208
	v_writelane_b32 v251, s23, 34
	v_writelane_b32 v251, s80, 35
	v_lshrrev_b32_e32 v184, 5, v170
	s_nop 0
	v_writelane_b32 v251, s81, 36
	v_writelane_b32 v251, s96, 37
	v_writelane_b32 v251, s83, 38
	v_writelane_b32 v251, s97, 39
	s_cbranch_scc1 .LBB9_413
	v_mbcnt_lo_u32_b32 v0, -1, 0
	v_mbcnt_hi_u32_b32 v0, -1, v0
	v_and_b32_e32 v1, 64, v0
	v_add_u32_e32 v1, 64, v1
	v_xor_b32_e32 v2, 1, v0
	v_cmp_lt_i32_e32 vcc, v2, v1
	s_bfe_u32 s0, s40, 0x20006
	v_writelane_b32 v251, s0, 40
	v_cndmask_b32_e32 v2, v0, v2, vcc
	v_lshlrev_b32_e32 v185, 2, v2
	v_xor_b32_e32 v2, 2, v0
	v_cmp_lt_i32_e32 vcc, v2, v1
	s_lshl_b32 s0, s50, 4
	s_and_b32 s33, s0, 0x3fffffc0
	v_cndmask_b32_e32 v2, v0, v2, vcc
	v_lshlrev_b32_e32 v186, 2, v2
	v_xor_b32_e32 v2, 4, v0
	v_cmp_lt_i32_e32 vcc, v2, v1
	s_cmpk_lt_u32 s40, 0x8c0
	s_cselect_b64 s[54:55], -1, 0
	v_cndmask_b32_e32 v2, v0, v2, vcc
	v_lshlrev_b32_e32 v187, 2, v2
	v_xor_b32_e32 v2, 8, v0
	v_cmp_lt_i32_e32 vcc, v2, v1
	s_or_b32 s2, s0, 63
	s_or_b32 s3, s33, 32
	v_cndmask_b32_e32 v2, v0, v2, vcc
	v_lshlrev_b32_e32 v188, 2, v2
	v_xor_b32_e32 v2, 16, v0
	v_cmp_lt_i32_e32 vcc, v2, v1
	v_or_b32_e32 v5, 32, v170
	v_lshlrev_b32_e32 v191, 4, v184
	v_cndmask_b32_e32 v2, v0, v2, vcc
	v_lshlrev_b32_e32 v189, 2, v2
	v_xor_b32_e32 v2, 32, v0
	v_cmp_lt_i32_e32 vcc, v2, v1
	v_mov_b32_e32 v1, 0
	v_mul_u32_u24_e32 v6, 0x110, v5
	v_cndmask_b32_e32 v0, v0, v2, vcc
	v_lshlrev_b32_e32 v190, 2, v0
	v_lshlrev_b32_e32 v0, 2, v184
	v_sub_u32_e32 v0, v171, v0
	v_cmp_lt_i32_e64 s[36:37], 10, v0
	v_cmp_gt_i32_e64 s[0:1], 1, v0
	v_cmp_gt_i32_e64 s[4:5], 2, v0
	v_writelane_b32 v251, s36, 41
	v_cmp_gt_i32_e64 s[6:7], 3, v0
	v_cmp_gt_i32_e64 s[8:9], 4, v0
	v_writelane_b32 v251, s37, 42
	v_cmp_lt_i32_e64 s[36:37], 15, v0
	v_cmp_gt_i32_e64 s[10:11], 9, v0
	v_cmp_gt_i32_e64 s[12:13], 10, v0
	v_writelane_b32 v251, s36, 43
	v_cmp_gt_i32_e64 s[14:15], 11, v0
	v_cmp_gt_i32_e64 s[16:17], 12, v0
	v_writelane_b32 v251, s37, 44
	v_cmp_lt_i32_e64 s[36:37], 16, v0
	v_cmp_gt_i32_e64 s[18:19], 17, v0
	v_cmp_gt_i32_e64 s[20:21], 18, v0
	v_writelane_b32 v251, s36, 45
	v_cmp_gt_i32_e64 s[22:23], 19, v0
	v_cmp_gt_i32_e64 s[24:25], 20, v0
	v_writelane_b32 v251, s37, 46
	v_cmp_lt_i32_e64 s[36:37], 17, v0
	v_cmp_gt_i32_e64 s[26:27], 25, v0
	v_cmp_gt_i32_e64 s[28:29], 26, v0
	v_writelane_b32 v251, s36, 47
	v_cmp_gt_i32_e64 s[30:31], 27, v0
	v_cmp_gt_i32_e64 s[34:35], 28, v0
	v_writelane_b32 v251, s37, 48
	v_cmp_lt_i32_e64 s[36:37], 18, v0
	v_cmp_lt_i32_e64 s[56:57], -1, v0
	v_cmp_lt_i32_e64 s[86:87], 0, v0
	v_writelane_b32 v251, s36, 49
	v_cmp_lt_i32_e64 s[60:61], 1, v0
	v_cmp_lt_i32_e64 s[62:63], 2, v0
	v_writelane_b32 v251, s37, 50
	v_cmp_lt_i32_e64 s[36:37], 23, v0
	v_cmp_lt_i32_e64 s[64:65], 7, v0
	v_cmp_lt_i32_e64 s[66:67], 8, v0
	v_writelane_b32 v251, s36, 51
	v_cmp_lt_i32_e64 s[72:73], 9, v0
	v_lshlrev_b32_e32 v4, 3, v184
	v_writelane_b32 v251, s37, 52
	v_cmp_lt_i32_e64 s[36:37], 24, v0
	v_mul_u32_u24_e32 v3, 0x110, v171
	v_lshlrev_b32_e32 v2, 10, v171
	v_writelane_b32 v251, s36, 53
	s_movk_i32 s52, 0x110
	v_add3_u32 v3, v3, v191, 0
	v_writelane_b32 v251, s37, 54
	v_cmp_lt_i32_e64 s[36:37], 25, v0
	v_lshlrev_b32_e32 v176, 1, v4
	s_mov_b32 s77, 0
	v_writelane_b32 v251, s36, 55
	v_add_u32_e32 v195, 0x4800, v3
	v_add_u32_e32 v198, 0xd400, v3
	v_writelane_b32 v251, s37, 56
	v_cmp_lt_i32_e64 s[36:37], 26, v0
	v_lshlrev_b32_e32 v0, 2, v170
	v_mad_u32_u24 v200, v5, s52, 0
	v_writelane_b32 v251, s36, 57
	v_mad_u32_u24 v201, v171, s52, 0
	s_mov_b64 s[68:69], 0
	v_writelane_b32 v251, s37, 58
	s_add_u32 s36, s90, 0x6200000
	v_writelane_b32 v251, s36, 59
	s_addc_u32 s36, s91, 0
	v_writelane_b32 v251, s36, 60
	s_add_u32 s36, s90, 0x7200000
	v_writelane_b32 v251, s36, 61
	s_addc_u32 s36, s91, 0
	v_writelane_b32 v251, s36, 62
	v_mov_b32_e32 v178, v176
	v_readlane_b32 s36, v251, 16
	s_add_u32 s36, s90, 0x4200000
	v_readlane_b32 s37, v251, 17
	v_readlane_b32 s38, v251, 18
	v_readlane_b32 s39, v251, 19
	v_readlane_b32 s40, v251, 20
	v_readlane_b32 s41, v251, 21
	v_readlane_b32 s42, v251, 22
	v_readlane_b32 s43, v251, 23
	v_readlane_b32 s44, v251, 24
	v_readlane_b32 s45, v251, 25
	v_readlane_b32 s46, v251, 26
	v_readlane_b32 s47, v251, 27
	v_readlane_b32 s48, v251, 28
	v_readlane_b32 s49, v251, 29
	v_readlane_b32 s50, v251, 30
	v_readlane_b32 s51, v251, 31
	v_writelane_b32 v251, s36, 63
	s_addc_u32 s36, s91, 0
	v_writelane_b32 v250, s36, 0
	s_add_u32 s36, s90, 0x6a00000
	v_writelane_b32 v250, s36, 1
	s_addc_u32 s36, s91, 0
	v_writelane_b32 v250, s36, 2
	s_add_u32 s36, s90, 0x7280000
	v_writelane_b32 v250, s36, 3
	s_addc_u32 s36, s91, 0
	v_writelane_b32 v250, s36, 4
	s_add_u32 s36, s90, 0x2000000
	v_writelane_b32 v250, s36, 5
	s_addc_u32 s36, s91, 0
	v_lshl_add_u64 v[172:173], s[40:41], 0, v[0:1]
	v_writelane_b32 v250, s36, 6
	s_add_i32 s40, 0, 0x11800
	s_add_i32 s76, 0, 0x16000
	v_writelane_b32 v250, s40, 7
	v_writelane_b32 v250, s76, 8
	v_writelane_b32 v250, s88, 9
	v_lshl_add_u64 v[174:175], s[42:43], 0, v[0:1]
	v_readlane_b32 s36, v251, 32
	v_writelane_b32 v250, s89, 10
	v_writelane_b32 v250, s90, 11
	v_writelane_b32 v250, s91, 12
	v_add3_u32 v0, v6, v191, 0
	v_mul_u32_u24_e32 v6, 0x90, v171
	v_writelane_b32 v250, s92, 13
	v_lshl_or_b32 v192, s36, 6, v170
	s_movk_i32 s37, 0x90
	v_add3_u32 v196, v6, v191, 0
	v_writelane_b32 v250, s93, 14
	v_add_u32_e32 v193, 0xfffffb80, v192
	v_add_u32_e32 v194, 0x4800, v0
	v_add_u32_e32 v197, 0xd400, v0
	v_add_u32_e32 v199, 0x8c00, v196
	v_mad_u32_u24 v202, v171, s37, 0
	v_mov_b32_e32 v179, v1
	v_lshlrev_b32_e32 v180, 1, v2
	v_mov_b32_e32 v181, v1
	s_mov_b32 s36, 0xf0f0f0f1
	s_movk_i32 s37, 0xffef
	s_movk_i32 s38, 0x490
	s_mov_b32 s39, 0x38e38e39
	v_readlane_b32 s42, v251, 39
	s_mov_b32 s98, 0
	v_writelane_b32 v250, s98, 24
	v_writelane_b32 v250, s94, 22
	v_writelane_b32 v250, s94, 23
	v_mov_b32_e32 v254, 0x24008
	ds_read_b32 v254, v254
	s_waitcnt lgkmcnt(0)
	v_readfirstlane_b32 s98, v254
	s_nop 3
	s_cmp_eq_u32 s98, 1
	s_cbranch_scc0 .Lrm_a
	s_cmpk_lg_i32 s94, 0x100
	s_cbranch_scc1 .Lrm_a
	s_and_b32 s98, s42, 7
	s_lshl_b32 s98, s98, 3
	s_bfe_u32 s99, s42, 0x30003
	s_or_b32 s98, s98, s99
	s_and_b32 vcc_lo, s98, 7
	s_lshl_b32 vcc_lo, vcc_lo, 3
	s_lshr_b32 vcc_hi, s98, 3
	s_or_b32 vcc_lo, vcc_lo, vcc_hi
	v_writelane_b32 v250, vcc_lo, 24
	s_lshr_b32 s99, s42, 6
	s_lshl_b32 s99, s99, 5
	s_lshr_b32 s42, s98, 4
	s_lshl_b32 s42, s42, 7
	s_or_b32 s42, s42, s99
	s_and_b32 s98, s98, 15
	s_lshl_b32 s98, s98, 1
	s_or_b32 s42, s42, s98
	s_mov_b32 s98, 1
	s_movk_i32 s99, 0x400
	v_writelane_b32 v250, s98, 22
	v_writelane_b32 v250, s99, 23

; __device__ __forceinline__ bool attn_unit(const Ptrs& P, LAS unsigned char* lds, int unit, int tid, int wave, int lane, bool pre, int nxt) {
;     ...
;     float mq = fabsf(P.qg[lane]), mk = fabsf(P.kg[lane]);
; #pragma unroll
;     for (int o = 1; o < 64; o <<= 1) { mq = fmaxf(mq, __shfl_xor(mq, o)); mk = fmaxf(mk, __shfl_xor(mk, o)); }
;     const float sink2 = P.sink[h] * LOG2E; const float mshift = fmaxf(64.0f * QSCALE * mq * mk, sink2);
.LBB9_329:
	v_readlane_b32 s98, v250, 24
	s_mov_b32 s99, 0
	s_nop 3

; #define AT_SYNC() do { asm volatile("s_waitcnt vmcnt(0) lgkmcnt(0)" ::: "memory"); __builtin_amdgcn_s_barrier(); asm volatile("" ::: "memory"); } while (0)
; __device__ __forceinline__ bool attn_unit(const Ptrs& P, LAS unsigned char* lds, int unit, int tid, int wave, int lane, bool pre, int nxt) {
;     ...
;     const float sink2 = P.sink[h] * LOG2E; const float mshift = fmaxf(64.0f * QSCALE * mq * mk, sink2);
;     bf16x8_t qf[2][4];
; #pragma unroll
;     for (int cb = 0; cb < 2; ++cb)
; #pragma unroll
;         for (int ds = 0; ds < 4; ++ds) qf[cb][ds] = __builtin_nontemporal_load((const bf16x8_t*)(Qb + (size_t)(32 * cb + r) * DM + 16 * ds + 8 * hh));
;     f32x16 o[2][2];
; #pragma unroll
;     for (int db = 0; db < 2; ++db)
; #pragma unroll
;         for (int cb = 0; cb < 2; ++cb)
; #pragma unroll
;             for (int i = 0; i < 16; ++i) o[db][cb][i] = 0.f;
;     float rs[2] = {0.f, 0.f};
;     f32x16 negm;
; #pragma unroll
;     for (int i = 0; i < 16; ++i) negm[i] = -mshift;
;     ...
;     if (!pre) { if (n == 0) AT_DMA(1); else AT_DMA(0); }
;     AT_SYNC();
;     const int n2 = nxt & 31; const bool pf = nxt >= 0 && n2 != 0;
.Lstl_done:
	v_writelane_b32 v250, s99, 24
	s_waitcnt vmcnt(8) lgkmcnt(0)
	v_max_f32_e32 v0, v11, v11
	v_max_f32_e32 v2, v9, v9
	v_max_f32_e32 v0, v2, v0
	v_max_f32_e32 v2, v10, v10
	v_max_f32_e32 v4, v8, v8
	v_max_f32_e32 v2, v4, v2
	v_mul_f32_e32 v0, 0x4138aa3b, v0
	v_mul_f32_e32 v0, v2, v0
	v_mul_f32_e32 v177, 0x3fb8aa3b, v3
	v_max_f32_e32 v203, v0, v177
	s_waitcnt vmcnt(0) lgkmcnt(0)
	s_barrier
	v_xor_b32_e32 v18, 0x80000000, v203
	v_cndmask_b32_e64 v0, 0, 1, s[54:55]
	v_mov_b32_e32 v19, v18
	v_mov_b32_e32 v20, v18
	v_mov_b32_e32 v21, v18
	v_mov_b32_e32 v22, v18
	v_mov_b32_e32 v23, v18
	v_mov_b32_e32 v24, v18
	v_mov_b32_e32 v25, v18
	v_mov_b32_e32 v26, v18
	v_mov_b32_e32 v27, v18
	v_mov_b32_e32 v28, v18
	v_mov_b32_e32 v29, v18
	v_mov_b32_e32 v30, v18
	v_mov_b32_e32 v31, v18
	v_mov_b32_e32 v32, v18
	v_mov_b32_e32 v33, v18
	s_cmp_eq_u32 s43, 0
	v_cmp_ne_u32_e64 s[68:69], 1, v0
	s_cbranch_scc1 .LBB9_350
	s_mov_b64 s[56:57], s[72:73]
	s_mov_b64 s[72:73], s[88:89]
	v_readlane_b32 s88, v250, 9
	s_and_b64 vcc, exec, s[68:69]
	s_mov_b64 s[60:61], s[64:65]
	s_mov_b64 s[62:63], s[66:67]
	s_mov_b64 s[64:65], s[40:41]
	s_mov_b64 s[66:67], s[0:1]
	s_mov_b64 s[0:1], s[4:5]
	s_mov_b64 s[4:5], s[6:7]
	s_mov_b64 s[6:7], s[8:9]
	s_mov_b64 s[8:9], s[10:11]
	s_mov_b64 s[10:11], s[12:13]
	s_mov_b64 s[12:13], s[14:15]
	s_mov_b64 s[14:15], s[16:17]
	s_mov_b64 s[16:17], s[18:19]
	s_mov_b64 s[18:19], s[20:21]
	s_mov_b64 s[20:21], s[22:23]
	s_mov_b64 s[22:23], s[24:25]
	s_mov_b64 s[24:25], s[26:27]
	s_mov_b64 s[26:27], s[28:29]
	s_mov_b64 s[28:29], s[30:31]
	s_mov_b64 s[30:31], s[34:35]
	s_mov_b64 s[34:35], s[80:81]
	v_readlane_b32 s89, v250, 10
	v_readlane_b32 s90, v250, 11
	v_readlane_b32 s91, v250, 12
	v_readlane_b32 s92, v250, 13
	v_readlane_b32 s93, v250, 14
	v_readlane_b32 s94, v250, 15
	v_readlane_b32 s95, v250, 16
	s_cbranch_vccnz .LBB9_338
	s_lshl_b32 s48, s43, 16
	s_add_u32 s84, s96, s48
	s_addc_u32 s85, s97, 0
	s_lshl_b32 s47, s47, 1
	s_add_u32 s74, s51, s47
	s_addc_u32 s75, s46, 0
	v_mov_b32_e32 v3, v193
	v_mov_b32_e32 v2, v192
	s_mov_b32 s47, s50
	s_branch .LBB9_334
